# P0: adaLN partial-sum loads all in flight + wave-major item dealing + pipelined silu(c) loads + no wait on icache warm-up
# speedup vs baseline: 1.0147x; 1.0147x over previous
.LBB0_2:
	s_load_dwordx4 s[84:87], s[0:1], 0x98
	s_movk_i32 s3, 0x168
	v_cmp_gt_u32_e32 vcc, s3, v170
	s_mov_b64 s[34:35], 0
	s_and_saveexec_b64 s[4:5], vcc
	s_cbranch_execz .LBB0_4
	s_getpc_b64 s[6:7]
	s_and_b32 s3, s6, -16
	s_bfe_u32 s6, s2, 0x50003
	s_mulk_i32 s6, 0x1680
	s_add_u32 s6, s6, s3
	v_lshlrev_b32_e32 v2, 4, v170
	v_mov_b32_e32 v3, 0
	s_addc_u32 s7, 0, s7
	v_lshl_add_u64 v[2:3], s[6:7], 0, v[2:3]
	global_load_dwordx4 v[16:19], v[2:3], off sc0 sc1

.LBB0_9:
	s_or_b64 exec, exec, s[4:5]
	v_readlane_b32 s3, v255, 0
	s_lshr_b32 s91, s3, 6
	s_add_u32 s94, s88, 0x280000
	s_addc_u32 s95, s89, 0
	s_cmp_lt_i32 s84, 1
	s_cselect_b64 s[4:5], -1, 0
	s_cmp_gt_i32 s85, 0
	s_cselect_b64 s[6:7], -1, 0
	s_and_b64 s[36:37], s[4:5], s[6:7]
	s_mov_b64 s[4:5], s[84:85]
	s_mov_b32 s6, s86
	s_load_dwordx16 s[64:79], s[0:1], 0x0
	v_writelane_b32 v255, s4, 6
	v_and_b32_e32 v242, 63, v170
	s_andn2_b64 vcc, exec, s[36:37]
	v_writelane_b32 v255, s5, 7
	v_writelane_b32 v255, s6, 8
	v_writelane_b32 v255, s7, 9
	v_lshlrev_b32_e32 v172, 2, v170
	v_writelane_b32 v255, s52, 10
	s_cbranch_vccnz .LBB0_50
	s_lshl_b32 s3, s33, 3
	s_abs_i32 s6, s3
	v_cvt_f32_u32_e32 v1, s6
	s_sub_i32 s5, 0, s6
	s_mul_i32 s4, s91, s33
	s_add_i32 s7, s4, s52
	v_rcp_iflag_f32_e32 v1, v1
	s_add_i32 s4, s7, s3
	v_mov_b32_e32 v173, 0
	v_add_u32_e32 v5, 0, v172
	v_mul_f32_e32 v1, 0x4f7ffffe, v1
	v_cvt_u32_f32_e32 v1, v1
	v_add_u32_e32 v4, 0xfffffe00, v170
	s_mov_b32 s84, s91
	s_waitcnt lgkmcnt(0)
	v_lshl_add_u64 v[2:3], s[66:67], 0, v[172:173]
	v_readfirstlane_b32 s8, v1
	s_mul_i32 s5, s5, s8
	s_mul_hi_u32 s5, s8, s5
	s_add_i32 s8, s8, s5
	s_mul_hi_u32 s5, s8, 0x300
	s_mul_i32 s5, s5, s6
	s_sub_i32 s5, 0x300, s5
	s_sub_i32 s9, s5, s6
	s_cmp_ge_u32 s5, s6
	s_cselect_b32 s5, s9, s5
	s_sub_i32 s9, s5, s6
	s_cmp_ge_u32 s5, s6
	s_cselect_b32 s5, s9, s5
	s_sub_i32 s4, s4, s5
	s_abs_i32 s43, s4
	s_ashr_i32 s42, s4, 31
	s_mul_hi_u32 s44, s43, s8
	v_add_u32_e32 v5, 0x20000, v5
	s_mov_b64 s[4:5], 0
	s_mov_b64 s[8:9], 0x800
	s_movk_i32 s10, 0x5ff
	global_load_dword v1, v[2:3], off
	global_load_dword v12, v[2:3], off offset:2048
	v_lshl_add_u64 v[2:3], v[2:3], 0, s[8:9]
	v_lshl_add_u64 v[2:3], v[2:3], 0, s[8:9]
	global_load_dword v13, v[2:3], off
	global_load_dword v14, v[2:3], off offset:2048
	s_waitcnt vmcnt(3)
	v_mul_f32_e32 v6, 0xbfb8aa3b, v1
	v_exp_f32_e32 v6, v6
	s_nop 0
	v_add_f32_e32 v6, 1.0, v6
	v_div_scale_f32 v7, s[12:13], v6, v6, v1
	v_rcp_f32_e32 v8, v7
	v_div_scale_f32 v9, vcc, v1, v6, v1
	v_fma_f32 v10, -v7, v8, 1.0
	v_fmac_f32_e32 v8, v10, v8
	v_mul_f32_e32 v10, v9, v8
	v_fma_f32 v11, -v7, v10, v9
	v_fmac_f32_e32 v10, v11, v8
	v_fma_f32 v7, -v7, v10, v9
	v_div_fmas_f32 v7, v7, v8, v10
	v_div_fixup_f32 v1, v7, v6, v1
	ds_write_b32 v5, v1
	s_waitcnt vmcnt(2)
	v_mul_f32_e32 v6, 0xbfb8aa3b, v12
	v_exp_f32_e32 v6, v6
	s_nop 0
	v_add_f32_e32 v6, 1.0, v6
	v_div_scale_f32 v7, s[12:13], v6, v6, v12
	v_rcp_f32_e32 v8, v7
	v_div_scale_f32 v9, vcc, v12, v6, v12
	v_fma_f32 v10, -v7, v8, 1.0
	v_fmac_f32_e32 v8, v10, v8
	v_mul_f32_e32 v10, v9, v8
	v_fma_f32 v11, -v7, v10, v9
	v_fmac_f32_e32 v10, v11, v8
	v_fma_f32 v7, -v7, v10, v9
	v_div_fmas_f32 v7, v7, v8, v10
	v_div_fixup_f32 v12, v7, v6, v12
	ds_write_b32 v5, v12 offset:2048
	s_waitcnt vmcnt(1)
	v_mul_f32_e32 v6, 0xbfb8aa3b, v13
	v_exp_f32_e32 v6, v6
	s_nop 0
	v_add_f32_e32 v6, 1.0, v6
	v_div_scale_f32 v7, s[12:13], v6, v6, v13
	v_rcp_f32_e32 v8, v7
	v_div_scale_f32 v9, vcc, v13, v6, v13
	v_fma_f32 v10, -v7, v8, 1.0
	v_fmac_f32_e32 v8, v10, v8
	v_mul_f32_e32 v10, v9, v8
	v_fma_f32 v11, -v7, v10, v9
	v_fmac_f32_e32 v10, v11, v8
	v_fma_f32 v7, -v7, v10, v9
	v_div_fmas_f32 v7, v7, v8, v10
	v_div_fixup_f32 v13, v7, v6, v13
	ds_write_b32 v5, v13 offset:4096
	s_waitcnt vmcnt(0)
	v_mul_f32_e32 v6, 0xbfb8aa3b, v14
	v_exp_f32_e32 v6, v6
	s_nop 0
	v_add_f32_e32 v6, 1.0, v6
	v_div_scale_f32 v7, s[12:13], v6, v6, v14
	v_rcp_f32_e32 v8, v7
	v_div_scale_f32 v9, vcc, v14, v6, v14
	v_fma_f32 v10, -v7, v8, 1.0
	v_fmac_f32_e32 v8, v10, v8
	v_mul_f32_e32 v10, v9, v8
	v_fma_f32 v11, -v7, v10, v9
	v_fmac_f32_e32 v10, v11, v8
	v_fma_f32 v7, -v7, v10, v9
	v_div_fmas_f32 v7, v7, v8, v10
	v_div_fixup_f32 v14, v7, v6, v14
	ds_write_b32 v5, v14 offset:6144
	s_cmpk_gt_i32 s7, 0x2ff
	s_waitcnt lgkmcnt(0)
	s_barrier
	s_cbranch_scc1 .LBB0_17
	v_mov_b32_e32 v75, 0
	v_lshlrev_b32_e32 v74, 3, v242
	v_lshlrev_b32_e32 v2, 1, v242
	s_add_u32 s45, s88, 0x100000
	v_lshl_add_u64 v[4:5], s[68:69], 0, v[74:75]
	s_mov_b64 s[4:5], 0xc0000
	s_addc_u32 s46, s89, 0
	v_lshl_add_u64 v[76:77], v[4:5], 0, s[4:5]
	s_mov_b32 s47, 0x42000
	s_mov_b32 s48, 0x48000
	s_mov_b32 s49, 0x4e000
	s_mov_b32 s50, 0x54000
	s_mov_b32 s51, 0x5a000
	s_mov_b32 s52, 0x60000
	s_mov_b32 s53, 0x66000
	s_mov_b32 s54, 0x6c000
	s_mov_b32 s55, 0x72000
	s_mov_b32 s56, 0x78000
	s_mov_b32 s57, 0x7e000
	s_mov_b32 s58, 0x84000
	s_mov_b32 s59, 0x8a000
	s_mov_b32 s60, 0x90000
	s_mov_b32 s61, 0x96000
	v_lshlrev_b32_e32 v158, 2, v2
	s_mov_b32 s62, 0x9c000
	s_mov_b32 s63, 0xa2000
	s_mov_b32 s66, 0xa8000
	s_mov_b32 s67, 0xae000
	s_mov_b32 s68, 0xb4000
	s_mov_b32 s69, 0xba000
	s_mov_b64 s[38:39], 0x180000

.LBB0_15:
	v_readfirstlane_b32 s8, v78
	v_readfirstlane_b32 s9, v79
	s_add_i32 s93, s91, s92
	s_add_i32 s10, s93, 0x20000
	v_mov_b32_e32 v1, s10
	s_sub_u32 s8, s8, 0xc0000
	s_subb_u32 s9, s9, 0
	s_nop 4
	global_load_dwordx2 v[6:7], v158, s[8:9] nt
	s_add_u32 s8, s8, 0x6000
	s_addc_u32 s9, s9, 0
	global_load_dwordx2 v[8:9], v158, s[8:9] nt
	s_add_u32 s8, s8, 0x6000
	s_addc_u32 s9, s9, 0
	global_load_dwordx2 v[10:11], v158, s[8:9] nt
	s_add_u32 s8, s8, 0x6000
	s_addc_u32 s9, s9, 0
	global_load_dwordx2 v[12:13], v158, s[8:9] nt
	s_add_u32 s8, s8, 0x6000
	s_addc_u32 s9, s9, 0
	global_load_dwordx2 v[14:15], v158, s[8:9] nt
	s_add_u32 s8, s8, 0x6000
	s_addc_u32 s9, s9, 0
	global_load_dwordx2 v[16:17], v158, s[8:9] nt
	s_add_u32 s8, s8, 0x6000
	s_addc_u32 s9, s9, 0
	global_load_dwordx2 v[18:19], v158, s[8:9] nt
	s_add_u32 s8, s8, 0x6000
	s_addc_u32 s9, s9, 0
	global_load_dwordx2 v[20:21], v158, s[8:9] nt
	s_add_u32 s8, s8, 0x6000
	s_addc_u32 s9, s9, 0
	global_load_dwordx2 v[22:23], v158, s[8:9] nt
	s_add_u32 s8, s8, 0x6000
	s_addc_u32 s9, s9, 0
	global_load_dwordx2 v[24:25], v158, s[8:9] nt
	s_add_u32 s8, s8, 0x6000
	s_addc_u32 s9, s9, 0
	global_load_dwordx2 v[26:27], v158, s[8:9] nt
	s_add_u32 s8, s8, 0x6000
	s_addc_u32 s9, s9, 0
	global_load_dwordx2 v[28:29], v158, s[8:9] nt
	s_add_u32 s8, s8, 0x6000
	s_addc_u32 s9, s9, 0
	global_load_dwordx2 v[30:31], v158, s[8:9] nt
	s_add_u32 s8, s8, 0x6000
	s_addc_u32 s9, s9, 0
	global_load_dwordx2 v[32:33], v158, s[8:9] nt
	s_add_u32 s8, s8, 0x6000
	s_addc_u32 s9, s9, 0
	global_load_dwordx2 v[34:35], v158, s[8:9] nt
	s_add_u32 s8, s8, 0x6000
	s_addc_u32 s9, s9, 0
	global_load_dwordx2 v[36:37], v158, s[8:9] nt
	s_add_u32 s8, s8, 0x6000
	s_addc_u32 s9, s9, 0
	global_load_dwordx2 v[38:39], v158, s[8:9] nt
	s_add_u32 s8, s8, 0x6000
	s_addc_u32 s9, s9, 0
	global_load_dwordx2 v[40:41], v158, s[8:9] nt
	s_add_u32 s8, s8, 0x6000
	s_addc_u32 s9, s9, 0
	global_load_dwordx2 v[42:43], v158, s[8:9] nt
	s_add_u32 s8, s8, 0x6000
	s_addc_u32 s9, s9, 0
	global_load_dwordx2 v[44:45], v158, s[8:9] nt
	s_add_u32 s8, s8, 0x6000
	s_addc_u32 s9, s9, 0
	global_load_dwordx2 v[46:47], v158, s[8:9] nt
	s_add_u32 s8, s8, 0x6000
	s_addc_u32 s9, s9, 0
	global_load_dwordx2 v[48:49], v158, s[8:9] nt
	s_add_u32 s8, s8, 0x6000
	s_addc_u32 s9, s9, 0
	global_load_dwordx2 v[50:51], v158, s[8:9] nt
	s_add_u32 s8, s8, 0x6000
	s_addc_u32 s9, s9, 0
	global_load_dwordx2 v[52:53], v158, s[8:9] nt
	s_add_u32 s8, s8, 0x6000
	s_addc_u32 s9, s9, 0
	global_load_dwordx2 v[54:55], v158, s[8:9] nt
	s_add_u32 s8, s8, 0x6000
	s_addc_u32 s9, s9, 0
	global_load_dwordx2 v[56:57], v158, s[8:9] nt
	s_add_u32 s8, s8, 0x6000
	s_addc_u32 s9, s9, 0
	global_load_dwordx2 v[58:59], v158, s[8:9] nt
	s_add_u32 s8, s8, 0x6000
	s_addc_u32 s9, s9, 0
	global_load_dwordx2 v[60:61], v158, s[8:9] nt
	s_add_u32 s8, s8, 0x6000
	s_addc_u32 s9, s9, 0
	global_load_dwordx2 v[62:63], v158, s[8:9] nt
	s_add_u32 s8, s8, 0x6000
	s_addc_u32 s9, s9, 0
	global_load_dwordx2 v[64:65], v158, s[8:9] nt
	s_add_u32 s8, s8, 0x6000
	s_addc_u32 s9, s9, 0
	global_load_dwordx2 v[66:67], v158, s[8:9] nt
	s_add_u32 s8, s8, 0x6000
	s_addc_u32 s9, s9, 0
	global_load_dwordx2 v[68:69], v158, s[8:9] nt
	s_add_u32 s8, s8, 0x6000
	s_addc_u32 s9, s9, 0
	global_load_dwordx2 v[70:71], v158, s[8:9] nt
	s_add_u32 s8, s8, 0x6000
	s_addc_u32 s9, s9, 0
	global_load_dwordx2 v[72:73], v158, s[8:9] nt
	s_add_u32 s8, s8, 0x6000
	s_addc_u32 s9, s9, 0
	global_load_dwordx2 v[80:81], v158, s[8:9] nt
	s_add_u32 s8, s8, 0x6000
	s_addc_u32 s9, s9, 0
	global_load_dwordx2 v[82:83], v158, s[8:9] nt
	s_add_u32 s8, s8, 0x6000
	s_addc_u32 s9, s9, 0
	global_load_dwordx2 v[84:85], v158, s[8:9] nt
	s_add_u32 s8, s8, 0x6000
	s_addc_u32 s9, s9, 0
	global_load_dwordx2 v[86:87], v158, s[8:9] nt
	s_add_u32 s8, s8, 0x6000
	s_addc_u32 s9, s9, 0
	global_load_dwordx2 v[88:89], v158, s[8:9] nt
	s_add_u32 s8, s8, 0x6000
	s_addc_u32 s9, s9, 0
	global_load_dwordx2 v[90:91], v158, s[8:9] nt
	s_add_u32 s8, s8, 0x6000
	s_addc_u32 s9, s9, 0
	global_load_dwordx2 v[92:93], v158, s[8:9] nt
	s_add_u32 s8, s8, 0x6000
	s_addc_u32 s9, s9, 0
	global_load_dwordx2 v[94:95], v158, s[8:9] nt
	s_add_u32 s8, s8, 0x6000
	s_addc_u32 s9, s9, 0
	global_load_dwordx2 v[96:97], v158, s[8:9] nt
	s_add_u32 s8, s8, 0x6000
	s_addc_u32 s9, s9, 0
	global_load_dwordx2 v[98:99], v158, s[8:9] nt
	s_add_u32 s8, s8, 0x6000
	s_addc_u32 s9, s9, 0
	global_load_dwordx2 v[100:101], v158, s[8:9] nt
	s_add_u32 s8, s8, 0x6000
	s_addc_u32 s9, s9, 0
	global_load_dwordx2 v[102:103], v158, s[8:9] nt
	s_add_u32 s8, s8, 0x6000
	s_addc_u32 s9, s9, 0
	global_load_dwordx2 v[104:105], v158, s[8:9] nt
	s_add_u32 s8, s8, 0x6000
	s_addc_u32 s9, s9, 0
	global_load_dwordx2 v[106:107], v158, s[8:9] nt
	s_add_u32 s8, s8, 0x6000
	s_addc_u32 s9, s9, 0
	global_load_dwordx2 v[108:109], v158, s[8:9] nt
	s_add_u32 s8, s8, 0x6000
	s_addc_u32 s9, s9, 0
	global_load_dwordx2 v[110:111], v158, s[8:9] nt
	s_add_u32 s8, s8, 0x6000
	s_addc_u32 s9, s9, 0
	global_load_dwordx2 v[112:113], v158, s[8:9] nt
	s_add_u32 s8, s8, 0x6000
	s_addc_u32 s9, s9, 0
	global_load_dwordx2 v[114:115], v158, s[8:9] nt
	s_add_u32 s8, s8, 0x6000
	s_addc_u32 s9, s9, 0
	global_load_dwordx2 v[116:117], v158, s[8:9] nt
	s_add_u32 s8, s8, 0x6000
	s_addc_u32 s9, s9, 0
	global_load_dwordx2 v[118:119], v158, s[8:9] nt
	s_add_u32 s8, s8, 0x6000
	s_addc_u32 s9, s9, 0
	global_load_dwordx2 v[120:121], v158, s[8:9] nt
	s_add_u32 s8, s8, 0x6000
	s_addc_u32 s9, s9, 0
	global_load_dwordx2 v[122:123], v158, s[8:9] nt
	s_add_u32 s8, s8, 0x6000
	s_addc_u32 s9, s9, 0
	global_load_dwordx2 v[124:125], v158, s[8:9] nt
	s_add_u32 s8, s8, 0x6000
	s_addc_u32 s9, s9, 0
	global_load_dwordx2 v[126:127], v158, s[8:9] nt
	s_add_u32 s8, s8, 0x6000
	s_addc_u32 s9, s9, 0
	global_load_dwordx2 v[128:129], v158, s[8:9] nt
	s_add_u32 s8, s8, 0x6000
	s_addc_u32 s9, s9, 0
	global_load_dwordx2 v[130:131], v158, s[8:9] nt
	s_add_u32 s8, s8, 0x6000
	s_addc_u32 s9, s9, 0
	global_load_dwordx2 v[132:133], v158, s[8:9] nt
	s_add_u32 s8, s8, 0x6000
	s_addc_u32 s9, s9, 0
	global_load_dwordx2 v[134:135], v158, s[8:9] nt
	s_add_u32 s8, s8, 0x6000
	s_addc_u32 s9, s9, 0
	global_load_dwordx2 v[136:137], v158, s[8:9] nt
	s_add_u32 s8, s8, 0x6000
	s_addc_u32 s9, s9, 0
	global_load_dwordx2 v[138:139], v158, s[8:9] nt
	ds_read_b128 v[140:143], v1
	ds_read_b128 v[144:147], v1 offset:4096
	ds_read_b128 v[148:151], v1 offset:16
	ds_read_b128 v[152:155], v1 offset:4112
	s_waitcnt vmcnt(60) lgkmcnt(2)
	v_pk_fma_f32 v[4:5], v[6:7], v[140:141], v[4:5] op_sel_hi:[1,0,1]
	v_pk_fma_f32 v[2:3], v[6:7], v[144:145], v[2:3] op_sel_hi:[1,0,1]
	v_pk_fma_f32 v[4:5], v[8:9], v[140:141], v[4:5] op_sel:[0,1,0]
	v_pk_fma_f32 v[2:3], v[8:9], v[144:145], v[2:3] op_sel:[0,1,0]
	v_pk_fma_f32 v[4:5], v[10:11], v[142:143], v[4:5] op_sel_hi:[1,0,1]
	v_pk_fma_f32 v[2:3], v[10:11], v[146:147], v[2:3] op_sel_hi:[1,0,1]
	v_pk_fma_f32 v[4:5], v[12:13], v[142:143], v[4:5] op_sel:[0,1,0]
	v_pk_fma_f32 v[2:3], v[12:13], v[146:147], v[2:3] op_sel:[0,1,0]
	ds_read_b128 v[140:143], v1 offset:32
	ds_read_b128 v[144:147], v1 offset:4128
	s_waitcnt vmcnt(56) lgkmcnt(2)
	v_pk_fma_f32 v[4:5], v[14:15], v[148:149], v[4:5] op_sel_hi:[1,0,1]
	v_pk_fma_f32 v[2:3], v[14:15], v[152:153], v[2:3] op_sel_hi:[1,0,1]
	v_pk_fma_f32 v[4:5], v[16:17], v[148:149], v[4:5] op_sel:[0,1,0]
	v_pk_fma_f32 v[2:3], v[16:17], v[152:153], v[2:3] op_sel:[0,1,0]
	v_pk_fma_f32 v[4:5], v[18:19], v[150:151], v[4:5] op_sel_hi:[1,0,1]
	v_pk_fma_f32 v[2:3], v[18:19], v[154:155], v[2:3] op_sel_hi:[1,0,1]
	v_pk_fma_f32 v[4:5], v[20:21], v[150:151], v[4:5] op_sel:[0,1,0]
	v_pk_fma_f32 v[2:3], v[20:21], v[154:155], v[2:3] op_sel:[0,1,0]
	ds_read_b128 v[148:151], v1 offset:48
	ds_read_b128 v[152:155], v1 offset:4144
	s_waitcnt vmcnt(52) lgkmcnt(2)
	v_pk_fma_f32 v[4:5], v[22:23], v[140:141], v[4:5] op_sel_hi:[1,0,1]
	v_pk_fma_f32 v[2:3], v[22:23], v[144:145], v[2:3] op_sel_hi:[1,0,1]
	v_pk_fma_f32 v[4:5], v[24:25], v[140:141], v[4:5] op_sel:[0,1,0]
	v_pk_fma_f32 v[2:3], v[24:25], v[144:145], v[2:3] op_sel:[0,1,0]
	v_pk_fma_f32 v[4:5], v[26:27], v[142:143], v[4:5] op_sel_hi:[1,0,1]
	v_pk_fma_f32 v[2:3], v[26:27], v[146:147], v[2:3] op_sel_hi:[1,0,1]
	v_pk_fma_f32 v[4:5], v[28:29], v[142:143], v[4:5] op_sel:[0,1,0]
	v_pk_fma_f32 v[2:3], v[28:29], v[146:147], v[2:3] op_sel:[0,1,0]
	ds_read_b128 v[140:143], v1 offset:64
	ds_read_b128 v[144:147], v1 offset:4160
	s_waitcnt vmcnt(48) lgkmcnt(2)
	v_pk_fma_f32 v[4:5], v[30:31], v[148:149], v[4:5] op_sel_hi:[1,0,1]
	v_pk_fma_f32 v[2:3], v[30:31], v[152:153], v[2:3] op_sel_hi:[1,0,1]
	v_pk_fma_f32 v[4:5], v[32:33], v[148:149], v[4:5] op_sel:[0,1,0]
	v_pk_fma_f32 v[2:3], v[32:33], v[152:153], v[2:3] op_sel:[0,1,0]
	v_pk_fma_f32 v[4:5], v[34:35], v[150:151], v[4:5] op_sel_hi:[1,0,1]
	v_pk_fma_f32 v[2:3], v[34:35], v[154:155], v[2:3] op_sel_hi:[1,0,1]
	v_pk_fma_f32 v[4:5], v[36:37], v[150:151], v[4:5] op_sel:[0,1,0]
	v_pk_fma_f32 v[2:3], v[36:37], v[154:155], v[2:3] op_sel:[0,1,0]
	ds_read_b128 v[148:151], v1 offset:80
	ds_read_b128 v[152:155], v1 offset:4176
	s_waitcnt vmcnt(44) lgkmcnt(2)
	v_pk_fma_f32 v[4:5], v[38:39], v[140:141], v[4:5] op_sel_hi:[1,0,1]
	v_pk_fma_f32 v[2:3], v[38:39], v[144:145], v[2:3] op_sel_hi:[1,0,1]
	v_pk_fma_f32 v[4:5], v[40:41], v[140:141], v[4:5] op_sel:[0,1,0]
	v_pk_fma_f32 v[2:3], v[40:41], v[144:145], v[2:3] op_sel:[0,1,0]
	v_pk_fma_f32 v[4:5], v[42:43], v[142:143], v[4:5] op_sel_hi:[1,0,1]
	v_pk_fma_f32 v[2:3], v[42:43], v[146:147], v[2:3] op_sel_hi:[1,0,1]
	v_pk_fma_f32 v[4:5], v[44:45], v[142:143], v[4:5] op_sel:[0,1,0]
	v_pk_fma_f32 v[2:3], v[44:45], v[146:147], v[2:3] op_sel:[0,1,0]
	ds_read_b128 v[140:143], v1 offset:96
	ds_read_b128 v[144:147], v1 offset:4192
	s_waitcnt vmcnt(40) lgkmcnt(2)
	v_pk_fma_f32 v[4:5], v[46:47], v[148:149], v[4:5] op_sel_hi:[1,0,1]
	v_pk_fma_f32 v[2:3], v[46:47], v[152:153], v[2:3] op_sel_hi:[1,0,1]
	v_pk_fma_f32 v[4:5], v[48:49], v[148:149], v[4:5] op_sel:[0,1,0]
	v_pk_fma_f32 v[2:3], v[48:49], v[152:153], v[2:3] op_sel:[0,1,0]
	v_pk_fma_f32 v[4:5], v[50:51], v[150:151], v[4:5] op_sel_hi:[1,0,1]
	v_pk_fma_f32 v[2:3], v[50:51], v[154:155], v[2:3] op_sel_hi:[1,0,1]
	v_pk_fma_f32 v[4:5], v[52:53], v[150:151], v[4:5] op_sel:[0,1,0]
	v_pk_fma_f32 v[2:3], v[52:53], v[154:155], v[2:3] op_sel:[0,1,0]
	ds_read_b128 v[148:151], v1 offset:112
	ds_read_b128 v[152:155], v1 offset:4208
	s_waitcnt vmcnt(36) lgkmcnt(2)
	v_pk_fma_f32 v[4:5], v[54:55], v[140:141], v[4:5] op_sel_hi:[1,0,1]
	v_pk_fma_f32 v[2:3], v[54:55], v[144:145], v[2:3] op_sel_hi:[1,0,1]
	v_pk_fma_f32 v[4:5], v[56:57], v[140:141], v[4:5] op_sel:[0,1,0]
	v_pk_fma_f32 v[2:3], v[56:57], v[144:145], v[2:3] op_sel:[0,1,0]
	v_pk_fma_f32 v[4:5], v[58:59], v[142:143], v[4:5] op_sel_hi:[1,0,1]
	v_pk_fma_f32 v[2:3], v[58:59], v[146:147], v[2:3] op_sel_hi:[1,0,1]
	v_pk_fma_f32 v[4:5], v[60:61], v[142:143], v[4:5] op_sel:[0,1,0]
	v_pk_fma_f32 v[2:3], v[60:61], v[146:147], v[2:3] op_sel:[0,1,0]
	ds_read_b128 v[140:143], v1 offset:128
	ds_read_b128 v[144:147], v1 offset:4224
	s_waitcnt vmcnt(32) lgkmcnt(2)
	v_pk_fma_f32 v[4:5], v[62:63], v[148:149], v[4:5] op_sel_hi:[1,0,1]
	v_pk_fma_f32 v[2:3], v[62:63], v[152:153], v[2:3] op_sel_hi:[1,0,1]
	v_pk_fma_f32 v[4:5], v[64:65], v[148:149], v[4:5] op_sel:[0,1,0]
	v_pk_fma_f32 v[2:3], v[64:65], v[152:153], v[2:3] op_sel:[0,1,0]
	v_pk_fma_f32 v[4:5], v[66:67], v[150:151], v[4:5] op_sel_hi:[1,0,1]
	v_pk_fma_f32 v[2:3], v[66:67], v[154:155], v[2:3] op_sel_hi:[1,0,1]
	v_pk_fma_f32 v[4:5], v[68:69], v[150:151], v[4:5] op_sel:[0,1,0]
	v_pk_fma_f32 v[2:3], v[68:69], v[154:155], v[2:3] op_sel:[0,1,0]
	ds_read_b128 v[148:151], v1 offset:144
	ds_read_b128 v[152:155], v1 offset:4240
	s_waitcnt vmcnt(28) lgkmcnt(2)
	v_pk_fma_f32 v[4:5], v[70:71], v[140:141], v[4:5] op_sel_hi:[1,0,1]
	v_pk_fma_f32 v[2:3], v[70:71], v[144:145], v[2:3] op_sel_hi:[1,0,1]
	v_pk_fma_f32 v[4:5], v[72:73], v[140:141], v[4:5] op_sel:[0,1,0]
	v_pk_fma_f32 v[2:3], v[72:73], v[144:145], v[2:3] op_sel:[0,1,0]
	v_pk_fma_f32 v[4:5], v[80:81], v[142:143], v[4:5] op_sel_hi:[1,0,1]
	v_pk_fma_f32 v[2:3], v[80:81], v[146:147], v[2:3] op_sel_hi:[1,0,1]
	v_pk_fma_f32 v[4:5], v[82:83], v[142:143], v[4:5] op_sel:[0,1,0]
	v_pk_fma_f32 v[2:3], v[82:83], v[146:147], v[2:3] op_sel:[0,1,0]
	ds_read_b128 v[140:143], v1 offset:160
	ds_read_b128 v[144:147], v1 offset:4256
	s_waitcnt vmcnt(24) lgkmcnt(2)
	v_pk_fma_f32 v[4:5], v[84:85], v[148:149], v[4:5] op_sel_hi:[1,0,1]
	v_pk_fma_f32 v[2:3], v[84:85], v[152:153], v[2:3] op_sel_hi:[1,0,1]
	v_pk_fma_f32 v[4:5], v[86:87], v[148:149], v[4:5] op_sel:[0,1,0]
	v_pk_fma_f32 v[2:3], v[86:87], v[152:153], v[2:3] op_sel:[0,1,0]
	v_pk_fma_f32 v[4:5], v[88:89], v[150:151], v[4:5] op_sel_hi:[1,0,1]
	v_pk_fma_f32 v[2:3], v[88:89], v[154:155], v[2:3] op_sel_hi:[1,0,1]
	v_pk_fma_f32 v[4:5], v[90:91], v[150:151], v[4:5] op_sel:[0,1,0]
	v_pk_fma_f32 v[2:3], v[90:91], v[154:155], v[2:3] op_sel:[0,1,0]
	ds_read_b128 v[148:151], v1 offset:176
	ds_read_b128 v[152:155], v1 offset:4272
	s_waitcnt vmcnt(20) lgkmcnt(2)
	v_pk_fma_f32 v[4:5], v[92:93], v[140:141], v[4:5] op_sel_hi:[1,0,1]
	v_pk_fma_f32 v[2:3], v[92:93], v[144:145], v[2:3] op_sel_hi:[1,0,1]
	v_pk_fma_f32 v[4:5], v[94:95], v[140:141], v[4:5] op_sel:[0,1,0]
	v_pk_fma_f32 v[2:3], v[94:95], v[144:145], v[2:3] op_sel:[0,1,0]
	v_pk_fma_f32 v[4:5], v[96:97], v[142:143], v[4:5] op_sel_hi:[1,0,1]
	v_pk_fma_f32 v[2:3], v[96:97], v[146:147], v[2:3] op_sel_hi:[1,0,1]
	v_pk_fma_f32 v[4:5], v[98:99], v[142:143], v[4:5] op_sel:[0,1,0]
	v_pk_fma_f32 v[2:3], v[98:99], v[146:147], v[2:3] op_sel:[0,1,0]
	ds_read_b128 v[140:143], v1 offset:192
	ds_read_b128 v[144:147], v1 offset:4288
	s_waitcnt vmcnt(16) lgkmcnt(2)
	v_pk_fma_f32 v[4:5], v[100:101], v[148:149], v[4:5] op_sel_hi:[1,0,1]
	v_pk_fma_f32 v[2:3], v[100:101], v[152:153], v[2:3] op_sel_hi:[1,0,1]
	v_pk_fma_f32 v[4:5], v[102:103], v[148:149], v[4:5] op_sel:[0,1,0]
	v_pk_fma_f32 v[2:3], v[102:103], v[152:153], v[2:3] op_sel:[0,1,0]
	v_pk_fma_f32 v[4:5], v[104:105], v[150:151], v[4:5] op_sel_hi:[1,0,1]
	v_pk_fma_f32 v[2:3], v[104:105], v[154:155], v[2:3] op_sel_hi:[1,0,1]
	v_pk_fma_f32 v[4:5], v[106:107], v[150:151], v[4:5] op_sel:[0,1,0]
	v_pk_fma_f32 v[2:3], v[106:107], v[154:155], v[2:3] op_sel:[0,1,0]
	ds_read_b128 v[148:151], v1 offset:208
	ds_read_b128 v[152:155], v1 offset:4304
	s_waitcnt vmcnt(12) lgkmcnt(2)
	v_pk_fma_f32 v[4:5], v[108:109], v[140:141], v[4:5] op_sel_hi:[1,0,1]
	v_pk_fma_f32 v[2:3], v[108:109], v[144:145], v[2:3] op_sel_hi:[1,0,1]
	v_pk_fma_f32 v[4:5], v[110:111], v[140:141], v[4:5] op_sel:[0,1,0]
	v_pk_fma_f32 v[2:3], v[110:111], v[144:145], v[2:3] op_sel:[0,1,0]
	v_pk_fma_f32 v[4:5], v[112:113], v[142:143], v[4:5] op_sel_hi:[1,0,1]
	v_pk_fma_f32 v[2:3], v[112:113], v[146:147], v[2:3] op_sel_hi:[1,0,1]
	v_pk_fma_f32 v[4:5], v[114:115], v[142:143], v[4:5] op_sel:[0,1,0]
	v_pk_fma_f32 v[2:3], v[114:115], v[146:147], v[2:3] op_sel:[0,1,0]
	ds_read_b128 v[140:143], v1 offset:224
	ds_read_b128 v[144:147], v1 offset:4320
	s_waitcnt vmcnt(8) lgkmcnt(2)
	v_pk_fma_f32 v[4:5], v[116:117], v[148:149], v[4:5] op_sel_hi:[1,0,1]
	v_pk_fma_f32 v[2:3], v[116:117], v[152:153], v[2:3] op_sel_hi:[1,0,1]
	v_pk_fma_f32 v[4:5], v[118:119], v[148:149], v[4:5] op_sel:[0,1,0]
	v_pk_fma_f32 v[2:3], v[118:119], v[152:153], v[2:3] op_sel:[0,1,0]
	v_pk_fma_f32 v[4:5], v[120:121], v[150:151], v[4:5] op_sel_hi:[1,0,1]
	v_pk_fma_f32 v[2:3], v[120:121], v[154:155], v[2:3] op_sel_hi:[1,0,1]
	v_pk_fma_f32 v[4:5], v[122:123], v[150:151], v[4:5] op_sel:[0,1,0]
	v_pk_fma_f32 v[2:3], v[122:123], v[154:155], v[2:3] op_sel:[0,1,0]
	ds_read_b128 v[148:151], v1 offset:240
	ds_read_b128 v[152:155], v1 offset:4336
	s_waitcnt vmcnt(4) lgkmcnt(2)
	v_pk_fma_f32 v[4:5], v[124:125], v[140:141], v[4:5] op_sel_hi:[1,0,1]
	v_pk_fma_f32 v[2:3], v[124:125], v[144:145], v[2:3] op_sel_hi:[1,0,1]
	v_pk_fma_f32 v[4:5], v[126:127], v[140:141], v[4:5] op_sel:[0,1,0]
	v_pk_fma_f32 v[2:3], v[126:127], v[144:145], v[2:3] op_sel:[0,1,0]
	v_pk_fma_f32 v[4:5], v[128:129], v[142:143], v[4:5] op_sel_hi:[1,0,1]
	v_pk_fma_f32 v[2:3], v[128:129], v[146:147], v[2:3] op_sel_hi:[1,0,1]
	v_pk_fma_f32 v[4:5], v[130:131], v[142:143], v[4:5] op_sel:[0,1,0]
	v_pk_fma_f32 v[2:3], v[130:131], v[146:147], v[2:3] op_sel:[0,1,0]
	s_waitcnt vmcnt(0) lgkmcnt(0)
	v_pk_fma_f32 v[4:5], v[132:133], v[148:149], v[4:5] op_sel_hi:[1,0,1]
	v_pk_fma_f32 v[2:3], v[132:133], v[152:153], v[2:3] op_sel_hi:[1,0,1]
	v_pk_fma_f32 v[4:5], v[134:135], v[148:149], v[4:5] op_sel:[0,1,0]
	v_pk_fma_f32 v[2:3], v[134:135], v[152:153], v[2:3] op_sel:[0,1,0]
	v_pk_fma_f32 v[4:5], v[136:137], v[150:151], v[4:5] op_sel_hi:[1,0,1]
	v_pk_fma_f32 v[2:3], v[136:137], v[154:155], v[2:3] op_sel_hi:[1,0,1]
	v_pk_fma_f32 v[4:5], v[138:139], v[150:151], v[4:5] op_sel:[0,1,0]
	v_pk_fma_f32 v[2:3], v[138:139], v[154:155], v[2:3] op_sel:[0,1,0]
	v_lshl_add_u64 v[78:79], v[78:79], 0, s[38:39]
	s_addk_i32 s92, 0x100
	s_cmpk_eq_i32 s92, 0x200
	s_cbranch_scc0 .LBB0_15
	s_lshl_b32 s4, s90, 2
	s_lshl_b32 s5, s87, 1
	s_add_i32 s8, s4, s5
	s_mul_i32 s5, s8, 0x6000
	s_mul_hi_i32 s4, s8, 0x6000
	s_add_u32 s5, s45, s5
	s_addc_u32 s9, s46, s4
	s_add_u32 s4, s5, s40
	s_addc_u32 s5, s9, s41
	global_store_dwordx2 v158, v[4:5], s[4:5]
	s_or_b32 s4, s8, 1
	s_mul_hi_i32 s5, s4, 0x6000
	s_mulk_i32 s4, 0x6000
	s_add_u32 s4, s45, s4
	s_addc_u32 s5, s46, s5
	s_add_u32 s4, s4, s40
	s_addc_u32 s5, s5, s41
	s_add_i32 s7, s7, s3
	s_cmpk_gt_i32 s7, 0x2ff
	global_store_dwordx2 v158, v[2:3], s[4:5]
	s_cbranch_scc0 .LBB0_14
